# ssd output stage: the 8 norm-weight loads of each row block issued through a register ring (one round trip instead of 8), on top of the pool-weight and residual-epilogue de-serialisation
# speedup vs baseline: 1.0027x; 1.0027x over previous
; __device__ __forceinline__ unsigned pk2(float lo, float hi) { return pg8::cvt_pk_bf16(lo, hi); }
; __device__ __forceinline__ float bperm(float v, int srclane) { return __builtin_bit_cast(float, __builtin_amdgcn_ds_bpermute(srclane << 2, __builtin_bit_cast(int, v))); }
; __device__ __forceinline__ void phase_ssdout(const Params& P, int l, unsigned char* lds, int tid, int lane, int wave, int G, const int bid) {
;     ...
;                 ssq += ssq_p; ssq += bperm(ssq, lane ^ 16); ssq += bperm(ssq, lane ^ 32); ssq = rsqrtf(ssq * (1.0f / 128.0f) + EPSN);
;                 const float* nwp = P.ssd_norm_w + l * 256 + (h - 1) * 64 + 4 * fq; bf16u* op = MIX + (size_t)r * DM + 256 + (h - 1) * 64 + 4 * fq;
; #pragma unroll
;                 for (int pt = 0; pt < 4; ++pt) { const f32x4 o0 = Yp[pt] * ssq * *(const f32x4*)(nwp + 16 * pt), o1 = Y[pt] * ssq * *(const f32x4*)(nwp + 64 + 16 * pt);
;                     u32x2 w0, w1; w0.x = pk2(o0.x, o0.y); w0.y = pk2(o0.z, o0.w); w1.x = pk2(o1.x, o1.y); w1.y = pk2(o1.z, o1.w);
;                     *(u32x2*)(op + 16 * pt) = w0; *(u32x2*)(op + 64 + 16 * pt) = w1; }
.LBB0_564:
	v_mov_b32_e32 v0, v17
	v_lshl_add_u64 v[16:17], s[48:49], 2, v[122:123]
	v_mov_b32_e32 v19, v22
	v_mov_b32_e32 v7, v24
	global_load_dwordx4 v[22:25], v[16:17], off
	v_add_f32_e32 v2, v112, v2
	ds_bpermute_b32 v4, v192, v2
	s_mov_b32 s33, 0x800000
	v_mov_b32_e32 v13, v10
	v_lshl_add_u64 v[10:11], s[48:49], 1, v[132:133]
	s_waitcnt lgkmcnt(0)
	v_add_f32_e32 v2, v2, v4
	ds_bpermute_b32 v4, v193, v2
	s_waitcnt lgkmcnt(0)
	v_add_f32_e32 v2, v2, v4
	v_fmamk_f32 v2, v2, 0x3c000000, v203
	v_cmp_gt_f32_e32 vcc, s33, v2
	v_mul_f32_e32 v4, 0x4b800000, v2
	s_nop 0
	v_cndmask_b32_e32 v2, v2, v4, vcc
	v_rsq_f32_e32 v2, v2
	s_nop 0
	v_mul_f32_e32 v4, 0x45800000, v2
	v_cndmask_b32_e32 v2, v2, v4, vcc
	v_pk_mul_f32 v[26:27], v[134:135], v[2:3] op_sel_hi:[1,0]
	v_pk_mul_f32 v[28:29], v[136:137], v[2:3] op_sel_hi:[1,0]
	v_mov_b32_e32 v4, v3
	v_pk_mul_f32 v[4:5], v[4:5], v[2:3] op_sel_hi:[1,0]
	global_load_dwordx4 v[232:235], v[16:17], off offset:256
	global_load_dwordx4 v[236:239], v[16:17], off offset:64
	global_load_dwordx4 v[240:243], v[16:17], off offset:320
	global_load_dwordx4 v[244:247], v[16:17], off offset:128
	global_load_dwordx4 v[248:251], v[16:17], off offset:384
	s_waitcnt vmcnt(0)
	v_pk_mul_f32 v[24:25], v[24:25], v[28:29]
	v_pk_mul_f32 v[22:23], v[22:23], v[26:27]
	v_pk_mul_f32 v[26:27], v[18:19], v[2:3] op_sel_hi:[1,0]
	v_pk_mul_f32 v[28:29], v[20:21], v[2:3] op_sel_hi:[1,0]
	v_cvt_pk_bf16_f32 v22, v22, v23
	v_cvt_pk_bf16_f32 v23, v24, v25
	v_pk_mul_f32 v[24:25], v[140:141], v[2:3] op_sel_hi:[1,0]
	s_nop 0
	v_pk_mul_f32 v[18:19], v[232:233], v[26:27]
	v_pk_mul_f32 v[20:21], v[234:235], v[28:29]
	global_load_dwordx4 v[232:235], v[16:17], off offset:192
	v_cvt_pk_bf16_f32 v18, v18, v19
	s_nop 0
	v_cvt_pk_bf16_f32 v19, v20, v21
	global_store_dwordx2 v[10:11], v[22:23], off
	global_store_dwordx2 v[10:11], v[18:19], off offset:128
	v_pk_mul_f32 v[22:23], v[138:139], v[2:3] op_sel_hi:[1,0]
	s_nop 0
	v_pk_mul_f32 v[20:21], v[238:239], v[24:25]
	v_pk_mul_f32 v[18:19], v[236:237], v[22:23]
	global_load_dwordx4 v[236:239], v[16:17], off offset:448
	v_pk_mul_f32 v[22:23], v[12:13], v[2:3] op_sel_hi:[1,0]
	v_pk_mul_f32 v[24:25], v[14:15], v[2:3] op_sel_hi:[1,0]
	v_cvt_pk_bf16_f32 v18, v18, v19
	v_cvt_pk_bf16_f32 v19, v20, v21
	v_pk_mul_f32 v[20:21], v[144:145], v[2:3] op_sel_hi:[1,0]
	s_nop 0
	v_pk_mul_f32 v[12:13], v[240:241], v[22:23]
	v_pk_mul_f32 v[14:15], v[242:243], v[24:25]
	v_cvt_pk_bf16_f32 v12, v12, v13
	s_nop 0
	v_cvt_pk_bf16_f32 v13, v14, v15
	global_store_dwordx2 v[10:11], v[18:19], off offset:32
	global_store_dwordx2 v[10:11], v[12:13], off offset:160
	v_pk_mul_f32 v[18:19], v[142:143], v[2:3] op_sel_hi:[1,0]
	s_nop 0
	v_pk_mul_f32 v[14:15], v[20:21], v[246:247]
	v_pk_mul_f32 v[12:13], v[18:19], v[244:245]
	v_pk_mul_f32 v[18:19], v[6:7], v[2:3] op_sel_hi:[1,0]
	v_pk_mul_f32 v[20:21], v[8:9], v[2:3] op_sel_hi:[1,0]
	v_cvt_pk_bf16_f32 v12, v12, v13
	v_cvt_pk_bf16_f32 v13, v14, v15
	v_pk_mul_f32 v[14:15], v[148:149], v[2:3] op_sel_hi:[1,0]
	s_nop 0
	v_pk_mul_f32 v[6:7], v[18:19], v[248:249]
	v_pk_mul_f32 v[8:9], v[20:21], v[250:251]
	v_cvt_pk_bf16_f32 v6, v6, v7
	s_nop 0
	v_cvt_pk_bf16_f32 v7, v8, v9
	global_store_dwordx2 v[10:11], v[12:13], off offset:64
	global_store_dwordx2 v[10:11], v[6:7], off offset:192
	v_pk_mul_f32 v[12:13], v[146:147], v[2:3] op_sel_hi:[1,0]
	s_nop 0
	s_waitcnt vmcnt(7)
	v_pk_mul_f32 v[8:9], v[14:15], v[234:235]
	v_pk_mul_f32 v[6:7], v[12:13], v[232:233]
	v_pk_mul_f32 v[12:13], v[0:1], v[2:3] op_sel_hi:[1,0]
	s_nop 0
	s_waitcnt vmcnt(4)
	v_pk_mul_f32 v[2:3], v[4:5], v[238:239]
	v_pk_mul_f32 v[0:1], v[12:13], v[236:237]
	v_cvt_pk_bf16_f32 v4, v6, v7
	v_cvt_pk_bf16_f32 v5, v8, v9
	s_nop 0
	v_cvt_pk_bf16_f32 v0, v0, v1
	v_cvt_pk_bf16_f32 v1, v2, v3
	global_store_dwordx2 v[10:11], v[4:5], off offset:96
	global_store_dwordx2 v[10:11], v[0:1], off offset:224

; __device__ __forceinline__ unsigned pk2(float lo, float hi) { return pg8::cvt_pk_bf16(lo, hi); }
; __device__ __forceinline__ float bperm(float v, int srclane) { return __builtin_bit_cast(float, __builtin_amdgcn_ds_bpermute(srclane << 2, __builtin_bit_cast(int, v))); }
; __device__ __forceinline__ void phase_ssdout(const Params& P, int l, unsigned char* lds, int tid, int lane, int wave, int G, const int bid) {
;     ...
;                 ssq += ssq_p; ssq += bperm(ssq, lane ^ 16); ssq += bperm(ssq, lane ^ 32); ssq = rsqrtf(ssq * (1.0f / 128.0f) + EPSN);
;                 const float* nwp = P.ssd_norm_w + l * 256 + (h - 1) * 64 + 4 * fq; bf16u* op = MIX + (size_t)r * DM + 256 + (h - 1) * 64 + 4 * fq;
; #pragma unroll
;                 for (int pt = 0; pt < 4; ++pt) { const f32x4 o0 = Yp[pt] * ssq * *(const f32x4*)(nwp + 16 * pt), o1 = Y[pt] * ssq * *(const f32x4*)(nwp + 64 + 16 * pt);
;                     u32x2 w0, w1; w0.x = pk2(o0.x, o0.y); w0.y = pk2(o0.z, o0.w); w1.x = pk2(o1.x, o1.y); w1.y = pk2(o1.z, o1.w);
;                     *(u32x2*)(op + 16 * pt) = w0; *(u32x2*)(op + 64 + 16 * pt) = w1; }
.LBB0_1470:
	v_mov_b32_e32 v0, v17
	v_lshl_add_u64 v[16:17], s[48:49], 2, v[122:123]
	v_mov_b32_e32 v19, v22
	v_mov_b32_e32 v7, v24
	global_load_dwordx4 v[22:25], v[16:17], off offset:1024
	v_add_f32_e32 v2, v112, v2
	ds_bpermute_b32 v4, v192, v2
	s_mov_b32 s33, 0x800000
	v_mov_b32_e32 v13, v10
	v_lshl_add_u64 v[10:11], s[48:49], 1, v[132:133]
	s_waitcnt lgkmcnt(0)
	v_add_f32_e32 v2, v2, v4
	ds_bpermute_b32 v4, v193, v2
	s_waitcnt lgkmcnt(0)
	v_add_f32_e32 v2, v2, v4
	v_fmamk_f32 v2, v2, 0x3c000000, v203
	v_cmp_gt_f32_e32 vcc, s33, v2
	v_mul_f32_e32 v4, 0x4b800000, v2
	s_nop 0
	v_cndmask_b32_e32 v2, v2, v4, vcc
	v_rsq_f32_e32 v2, v2
	s_nop 0
	v_mul_f32_e32 v4, 0x45800000, v2
	v_cndmask_b32_e32 v2, v2, v4, vcc
	v_pk_mul_f32 v[26:27], v[134:135], v[2:3] op_sel_hi:[1,0]
	v_pk_mul_f32 v[28:29], v[136:137], v[2:3] op_sel_hi:[1,0]
	v_mov_b32_e32 v4, v3
	v_pk_mul_f32 v[4:5], v[4:5], v[2:3] op_sel_hi:[1,0]
	global_load_dwordx4 v[232:235], v[16:17], off offset:1280
	global_load_dwordx4 v[236:239], v[16:17], off offset:1088
	global_load_dwordx4 v[240:243], v[16:17], off offset:1344
	global_load_dwordx4 v[244:247], v[16:17], off offset:1152
	global_load_dwordx4 v[248:251], v[16:17], off offset:1408
	s_waitcnt vmcnt(0)
	v_pk_mul_f32 v[24:25], v[24:25], v[28:29]
	v_pk_mul_f32 v[22:23], v[22:23], v[26:27]
	v_pk_mul_f32 v[26:27], v[18:19], v[2:3] op_sel_hi:[1,0]
	v_pk_mul_f32 v[28:29], v[20:21], v[2:3] op_sel_hi:[1,0]
	v_cvt_pk_bf16_f32 v22, v22, v23
	v_cvt_pk_bf16_f32 v23, v24, v25
	v_pk_mul_f32 v[24:25], v[140:141], v[2:3] op_sel_hi:[1,0]
	s_nop 0
	v_pk_mul_f32 v[18:19], v[232:233], v[26:27]
	v_pk_mul_f32 v[20:21], v[234:235], v[28:29]
	global_load_dwordx4 v[232:235], v[16:17], off offset:1216
	v_cvt_pk_bf16_f32 v18, v18, v19
	s_nop 0
	v_cvt_pk_bf16_f32 v19, v20, v21
	global_store_dwordx2 v[10:11], v[22:23], off
	global_store_dwordx2 v[10:11], v[18:19], off offset:128
	v_pk_mul_f32 v[22:23], v[138:139], v[2:3] op_sel_hi:[1,0]
	s_nop 0
	v_pk_mul_f32 v[20:21], v[238:239], v[24:25]
	v_pk_mul_f32 v[18:19], v[236:237], v[22:23]
	global_load_dwordx4 v[236:239], v[16:17], off offset:1472
	v_pk_mul_f32 v[22:23], v[12:13], v[2:3] op_sel_hi:[1,0]
	v_pk_mul_f32 v[24:25], v[14:15], v[2:3] op_sel_hi:[1,0]
	v_cvt_pk_bf16_f32 v18, v18, v19
	v_cvt_pk_bf16_f32 v19, v20, v21
	v_pk_mul_f32 v[20:21], v[144:145], v[2:3] op_sel_hi:[1,0]
	s_nop 0
	v_pk_mul_f32 v[12:13], v[240:241], v[22:23]
	v_pk_mul_f32 v[14:15], v[242:243], v[24:25]
	v_cvt_pk_bf16_f32 v12, v12, v13
	s_nop 0
	v_cvt_pk_bf16_f32 v13, v14, v15
	global_store_dwordx2 v[10:11], v[18:19], off offset:32
	global_store_dwordx2 v[10:11], v[12:13], off offset:160
	v_pk_mul_f32 v[18:19], v[142:143], v[2:3] op_sel_hi:[1,0]
	s_nop 0
	v_pk_mul_f32 v[14:15], v[20:21], v[246:247]
	v_pk_mul_f32 v[12:13], v[18:19], v[244:245]
	v_pk_mul_f32 v[18:19], v[6:7], v[2:3] op_sel_hi:[1,0]
	v_pk_mul_f32 v[20:21], v[8:9], v[2:3] op_sel_hi:[1,0]
	v_cvt_pk_bf16_f32 v12, v12, v13
	v_cvt_pk_bf16_f32 v13, v14, v15
	v_pk_mul_f32 v[14:15], v[148:149], v[2:3] op_sel_hi:[1,0]
	s_nop 0
	v_pk_mul_f32 v[6:7], v[18:19], v[248:249]
	v_pk_mul_f32 v[8:9], v[20:21], v[250:251]
	v_cvt_pk_bf16_f32 v6, v6, v7
	s_nop 0
	v_cvt_pk_bf16_f32 v7, v8, v9
	global_store_dwordx2 v[10:11], v[12:13], off offset:64
	global_store_dwordx2 v[10:11], v[6:7], off offset:192
	v_pk_mul_f32 v[12:13], v[146:147], v[2:3] op_sel_hi:[1,0]
	s_nop 0
	s_waitcnt vmcnt(7)
	v_pk_mul_f32 v[8:9], v[14:15], v[234:235]
	v_pk_mul_f32 v[6:7], v[12:13], v[232:233]
	v_pk_mul_f32 v[12:13], v[0:1], v[2:3] op_sel_hi:[1,0]
	s_nop 0
	s_waitcnt vmcnt(4)
	v_pk_mul_f32 v[2:3], v[4:5], v[238:239]
	v_pk_mul_f32 v[0:1], v[12:13], v[236:237]
	v_cvt_pk_bf16_f32 v4, v6, v7
	v_cvt_pk_bf16_f32 v5, v8, v9
	s_nop 0
	v_cvt_pk_bf16_f32 v0, v0, v1
	v_cvt_pk_bf16_f32 v1, v2, v3
	global_store_dwordx2 v[10:11], v[4:5], off offset:96
	global_store_dwordx2 v[10:11], v[0:1], off offset:224
